# P4->P5 barrier XCD-local as well: split-phase (each XCD counts itself past P4; the P5->P6 barrier's last arriver checks the count before releasing)
# speedup vs baseline: 1.0015x; 1.0015x over previous
; #define LAS __attribute__((address_space(3)))
;     ...
;   int tid_ = threadIdx.x; asm volatile("" : "+v"(tid_)); const int tid = tid_, wid = __builtin_amdgcn_readfirstlane(tid >> 6), lane = tid & 63, fr = lane & 15, fq = lane >> 4;
;   const bf16_t* Qr = (const bf16_t*)(ws + OFF_QR); const bf16_t* Kr = (const bf16_t*)(ws + OFF_KR); const bf16_t* Vrt = (const bf16_t*)(ws + OFF_VRT);
;   const bf16_t* RT = (const bf16_t*)p.out;
;   bf16_t* G = (bf16_t*)(ws + OFF_G);
;     ...
;   for (int u = blockIdx.x; u < 1024; u += gridDim.x) {
;     const int bh = u >> 6, c = u & 63, h = bh & 3, b = bh >> 2;
;     const float gam = exp2f(lg2gamma(h));
;     {
;       const u32x4* qg = (const u32x4*)(Qr + (long)(bh * 64 + c) * 16384); const u32x4* kg = (const u32x4*)(Kr + (long)(bh * 64 + c) * 16384);
;       u32x4 qv[4], kv[4];
; #pragma unroll
;       for (int i = 0; i < 4; ++i) { qv[i] = qg[tid + i * NTHREADS]; kv[i] = kg[tid + i * NTHREADS]; }
; #pragma unroll
;       for (int i = 0; i < 4; ++i) { *(LAS u32x4*)(shm + RO_Q + (tid + i * NTHREADS) * 16) = qv[i]; *(LAS u32x4*)(shm + RO_K + (tid + i * NTHREADS) * 16) = kv[i]; }
;     }
;     bf16x8 rf[2][4], vf[2][4];
;     {
;       const bf16_t* rp = RT + (long)(bh * 64 + c) * 32768 + (2 * wid) * 2048 + lane * 8;
;       const bf16_t* vp = Vrt + (long)(bh * 64 + c) * 32768 + (2 * wid) * 2048 + lane * 8;
.LBB0_726:
	s_or_b64 exec, exec, s[6:7]
	s_and_saveexec_b64 s[98:99], s[94:95]
	v_add_u32_e32 v248, -1, v240
	v_and_b32_e32 v248, v248, v240
	v_add_u32_e32 v249, -1, v241
	v_and_b32_e32 v249, v249, v241
	v_or_b32_e32 v248, v248, v249
	v_add_u32_e32 v249, -1, v242
	v_and_b32_e32 v249, v249, v242
	v_or_b32_e32 v248, v248, v249
	v_add_u32_e32 v249, -1, v243
	v_and_b32_e32 v249, v249, v243
	v_or_b32_e32 v248, v248, v249
	v_add_u32_e32 v249, -1, v244
	v_and_b32_e32 v249, v249, v244
	v_or_b32_e32 v248, v248, v249
	v_add_u32_e32 v249, -1, v245
	v_and_b32_e32 v249, v249, v245
	v_or_b32_e32 v248, v248, v249
	v_add_u32_e32 v249, -1, v246
	v_and_b32_e32 v249, v249, v246
	v_or_b32_e32 v248, v248, v249
	v_add_u32_e32 v249, -1, v247
	v_and_b32_e32 v249, v249, v247
	v_or_b32_e32 v248, v248, v249
	v_cmp_eq_u32_e32 vcc, 0, v248
	s_nop 1
	v_cndmask_b32_e64 v249, 0, 1, vcc
	v_mov_b32_e32 v253, 0x23ff8
	ds_write_b32 v253, v249
	s_or_b64 exec, exec, s[98:99]
	s_add_u32 s22, s26, 0x2300000
	s_addc_u32 s23, s27, 0
	s_waitcnt vmcnt(27) lgkmcnt(0)
	v_mov_b32_e32 v0, v194
	s_add_u32 s68, s26, 0xc300000
	s_barrier
	s_addc_u32 s69, s27, 0
	s_andn2_b64 vcc, exec, s[0:1]
	v_readfirstlane_b32 s0, v0
	s_cbranch_vccnz .LBB0_755
	s_ashr_i32 s12, s0, 6
	s_lshl_b32 s10, s12, 12
	s_ashr_i32 s11, s10, 31
	s_add_i32 s1, 0, 0x18000
	s_lshl_b64 s[6:7], s[10:11], 1
	s_add_u32 s8, s24, s6
	s_addc_u32 s9, s25, s7
	v_and_b32_e32 v1, 63, v0
	s_waitcnt vmcnt(14)
	v_mov_b32_e32 v91, 0
	s_add_u32 s6, s3, s6
	v_lshlrev_b32_e32 v88, 4, v1
	v_mov_b32_e32 v89, v91
	s_addc_u32 s7, s66, s7
	s_lshl_b32 s3, s12, 4
	s_ashr_i32 s0, s0, 31
	s_waitcnt vmcnt(12)
	v_lshl_add_u64 v[94:95], s[6:7], 0, v[88:89]
	s_or_b32 s6, s3, 15
	s_lshr_b32 s0, s0, 27
	v_and_b32_e32 v3, 15, v0
	s_add_i32 s0, s6, s0
	v_lshl_add_u64 v[92:93], s[8:9], 0, v[88:89]
	s_ashr_i32 s39, s0, 5
	v_or_b32_e32 v89, s3, v3
	s_add_i32 s3, s10, 0
	s_cmpk_gt_i32 s6, 0xffe0
	s_movk_i32 s0, 0x80
	s_cselect_b64 s[40:41], -1, 0
	v_cmp_gt_u32_e64 s[6:7], 16, v1
	v_cmp_gt_i32_e64 s[8:9], s0, v0
	v_lshlrev_b32_e32 v1, 3, v0
	s_add_i32 s11, 0, 0x1a000
	s_mul_i32 s0, s12, 0x2800
	s_waitcnt vmcnt(6)
	v_add_u32_e32 v121, s1, v1
	v_add_u32_e32 v122, s11, v1
	s_add_i32 s13, s0, 0
	v_and_b32_e32 v4, 24, v1
	v_and_b32_e32 v1, 3, v0
	v_lshrrev_b32_e32 v2, 1, v0
	v_lshl_add_u32 v13, v1, 4, s13
	v_lshlrev_b32_e32 v6, 3, v1
	v_ashrrev_i32_e32 v1, 31, v0
	v_lshlrev_b32_e32 v7, 4, v0
	v_and_b32_e32 v9, 24, v2
	v_lshlrev_b32_e32 v2, 8, v0
	v_bfe_u32 v10, v0, 2, 4
	v_lshlrev_b64 v[0:1], 4, v[0:1]
	v_lshlrev_b32_e32 v5, 3, v3
	s_lshl_b32 s30, s12, 10
	v_add_u32_e32 v11, s13, v9
	s_lshl_b32 s0, s12, 5
	v_lshl_add_u64 v[96:97], s[22:23], 0, v[0:1]
	v_lshl_add_u64 v[0:1], s[26:27], 0, v[0:1]
	s_mov_b64 s[12:13], 0x4300000
	v_add_u32_e32 v131, 0, v88
	v_add_u32_e32 v120, s1, v5
	v_add_u32_e32 v123, s11, v5
	v_lshlrev_b32_e32 v8, 10, v10
	v_or_b32_e32 v5, 16, v10
	v_lshl_add_u64 v[98:99], v[0:1], 0, s[12:13]
	v_add_u32_e32 v0, s10, v131
	s_ashr_i32 s1, s0, 31
	v_and_b32_e32 v2, 0x3c00, v2
	v_mul_u32_u24_e32 v15, 0x50, v10
	v_mul_u32_u24_e32 v3, 0x50, v3
	v_mul_u32_u24_e32 v17, 0x50, v5
	v_lshlrev_b32_e32 v10, 10, v5
	v_or_b32_e32 v12, 0x8000, v8
	v_or_b32_e32 v14, 0xc000, v8
	v_or_b32_e32 v16, 0x10000, v8
	v_or_b32_e32 v18, 0x14000, v8
	v_or_b32_e32 v20, 0x18000, v8
	v_or_b32_e32 v22, 0x1c000, v8
	v_add_u32_e32 v132, 0x10000, v0
	v_mbcnt_lo_u32_b32 v0, -1, 0
	s_mov_b32 s18, 0
	s_mov_b32 s19, 0x18000
	s_waitcnt vmcnt(4)
	v_add_u32_e32 v124, 0x80, v123
	v_add_u32_e32 v125, 0x100, v123
	v_add_u32_e32 v126, 0x180, v123
	v_add_u32_e32 v127, 0x200, v123
	v_add_u32_e32 v128, 0x280, v123
	v_add_u32_e32 v129, 0x300, v123
	v_add_u32_e32 v130, 0x380, v123
	s_mov_b32 s31, 0x8000
	s_mov_b32 s38, 0x10000
	s_add_i32 s39, s39, 1
	v_or_b32_e32 v133, 7, v9
	v_add_u32_e32 v134, 0x8000, v131
	v_add_u32_e32 v135, 0, v7
	s_movk_i32 s43, 0x1000
	v_mbcnt_hi_u32_b32 v136, -1, v0
	s_mov_b32 s42, 0x3b800000
	v_add_u32_e32 v137, v11, v3
	s_lshl_b64 s[44:45], s[0:1], 1
	v_lshlrev_b32_e32 v90, 1, v4
	v_lshlrev_b32_e32 v100, 1, v2
	s_mov_b32 s48, 0x20000
	s_mov_b32 s49, 0x28000
	s_mov_b32 s50, 0x30000
	s_mov_b32 s51, 0x38000
	v_lshlrev_b32_e32 v102, 1, v6
	v_add_u32_e32 v138, v13, v15
	v_lshlrev_b32_e32 v104, 1, v8
	v_add_u32_e32 v139, v13, v17
	v_lshlrev_b32_e32 v106, 1, v10
	v_lshlrev_b32_e32 v108, 1, v12
	v_lshlrev_b32_e32 v110, 1, v14
	v_lshlrev_b32_e32 v112, 1, v16
	v_lshlrev_b32_e32 v114, 1, v18
	v_lshlrev_b32_e32 v116, 1, v20
	v_lshlrev_b32_e32 v118, 1, v22
	v_mov_b32_e32 v140, 0x3f7f0000
	v_mov_b32_e32 v141, 0x3f7e0000
	s_mov_b32 s46, s2
	s_branch .LBB0_729

; DI unsigned xb_ld(unsigned* p) { return __hip_atomic_load(p, __ATOMIC_RELAXED, __HIP_MEMORY_SCOPE_AGENT); }
; DI unsigned xb_add(unsigned* p, unsigned v) { return __hip_atomic_fetch_add(p, v, __ATOMIC_RELAXED, __HIP_MEMORY_SCOPE_AGENT); }
; #define XB_SPIN(cond, bar) do { unsigned _sp = 0; while (cond) { __builtin_amdgcn_s_sleep(1); \
;     if ((++_sp & 255u) == 0u) { if (xb_ld(&(bar)[XB_TMO])) break; if (_sp > XB_SPIN_CAP) { atomicAdd(&(bar)[XB_TMO], 1u); break; } } } } while (0)
; DI void xcd_barrier(const XcdBarrier& b) {
;     ...
;     const unsigned old = xb_add(&bar[XB_XSUB(b.x)], 1u);
;     const unsigned gen = old / nloc;
;     if (old + 1u == (gen + 1u) * nloc) {
;       __builtin_amdgcn_fence(__ATOMIC_RELEASE, "agent");
;       asm volatile("s_waitcnt vmcnt(0)" ::: "memory");
;       const unsigned og = xb_add(&bar[XB_TOP], 1u);
;       const unsigned tg = og / nx;
;       if (og + 1u == (tg + 1u) * nx) xb_add(&bar[XB_TOPGEN], 1u);
;       else XB_SPIN(xb_ld(&bar[XB_TOPGEN]) == tg, bar);
;       __builtin_amdgcn_fence(__ATOMIC_ACQUIRE, "agent");
;       xb_add(&bar[XB_XGEN(b.x)], 1u);
.LBB0_914:
	s_andn2_saveexec_b64 s[8:9], s[8:9]
	s_cbranch_execz .LBB0_934
	s_mov_b64 s[8:9], exec
	v_mov_b32_e32 v253, 0x23ff8
	ds_read_b32 v252, v253
	buffer_wbl2 sc1
	s_waitcnt lgkmcnt(0)
	s_waitcnt vmcnt(0)
	v_cmp_ne_u32_e32 vcc, 0, v252
	s_cbranch_vccz .Lsp5_full
	v_mov_b32_e32 v253, 0x1e7e1320
	v_mov_b32_e32 v254, 1
	global_atomic_add v253, v254, s[26:27]
	s_branch .LBB0_931
.Lsp5_full:
	v_mbcnt_lo_u32_b32 v1, s8, 0
	v_mbcnt_hi_u32_b32 v1, s9, v1
	v_cmp_eq_u32_e32 vcc, 0, v1
	s_and_saveexec_b64 s[10:11], vcc
	s_cbranch_execz .LBB0_917
	s_bcnt1_i32_b64 s8, s[8:9]
	v_mov_b32_e32 v2, 0x1e7e4000
	v_mov_b32_e32 v3, s8
	global_atomic_add v2, v2, v3, s[26:27] offset:1024 sc0

; DI unsigned xb_ld(unsigned* p) { return __hip_atomic_load(p, __ATOMIC_RELAXED, __HIP_MEMORY_SCOPE_AGENT); }
; DI unsigned xb_add(unsigned* p, unsigned v) { return __hip_atomic_fetch_add(p, v, __ATOMIC_RELAXED, __HIP_MEMORY_SCOPE_AGENT); }
; #define XB_SPIN(cond, bar) do { unsigned _sp = 0; while (cond) { __builtin_amdgcn_s_sleep(1); \
;     if ((++_sp & 255u) == 0u) { if (xb_ld(&(bar)[XB_TMO])) break; if (_sp > XB_SPIN_CAP) { atomicAdd(&(bar)[XB_TMO], 1u); break; } } } } while (0)
; DI void xcd_barrier(const XcdBarrier& b) {
;     ...
;     const unsigned old = xb_add(&bar[XB_XSUB(b.x)], 1u);
;     const unsigned gen = old / nloc;
;     if (old + 1u == (gen + 1u) * nloc) {
;       __builtin_amdgcn_fence(__ATOMIC_RELEASE, "agent");
;       asm volatile("s_waitcnt vmcnt(0)" ::: "memory");
;       const unsigned og = xb_add(&bar[XB_TOP], 1u);
;       const unsigned tg = og / nx;
;       if (og + 1u == (tg + 1u) * nx) xb_add(&bar[XB_TOPGEN], 1u);
;       else XB_SPIN(xb_ld(&bar[XB_TOPGEN]) == tg, bar);
;       __builtin_amdgcn_fence(__ATOMIC_ACQUIRE, "agent");
;       xb_add(&bar[XB_XGEN(b.x)], 1u);
;       asm volatile("s_waitcnt vmcnt(0)" ::: "memory");
;     } else {
;       XB_SPIN(xb_ld(&bar[XB_XGEN(b.x)]) == gen, bar);
.LBB0_1016:
	s_andn2_saveexec_b64 s[6:7], s[6:7]
	s_cbranch_execz .LBB0_1036
	s_mov_b64 s[6:7], exec
	v_mov_b32_e32 v253, 0x23ff8
	ds_read_b32 v252, v253
	v_mov_b32_e32 v253, 0x1e7e1320
	global_load_dword v254, v253, s[26:27] sc1
	buffer_wbl2 sc1
	s_waitcnt lgkmcnt(0)
	s_waitcnt vmcnt(0)
	v_cmp_ne_u32_e32 vcc, 0, v252
	s_cbranch_vccz .Lsp6_full
.Lsp6_chk:
	v_cmp_ge_u32_e32 vcc, v254, v0
	s_cbranch_vccnz .LBB0_1033
	s_sleep 1
	global_load_dword v254, v253, s[26:27] sc1
	s_waitcnt vmcnt(0)
	s_branch .Lsp6_chk
.Lsp6_full:
	v_mbcnt_lo_u32_b32 v1, s6, 0
	v_mbcnt_hi_u32_b32 v1, s7, v1
	v_cmp_eq_u32_e32 vcc, 0, v1
	s_and_saveexec_b64 s[8:9], vcc
	s_cbranch_execz .LBB0_1019
	s_bcnt1_i32_b64 s3, s[6:7]
	v_mov_b32_e32 v2, 0x1e7e4000
	v_mov_b32_e32 v3, s3
	global_atomic_add v2, v2, v3, s[26:27] offset:1024 sc0
